# v28 + FFN-in fast path: up operand read last and waited at its first consumer (counted lgkmcnt), strategy 7.2
# baseline (speedup 1.0000x reference)
; DI void stf8(float* p, const F8& f) { *(float4*)p = make_float4(f.v[0], f.v[1], f.v[2], f.v[3]); *(float4*)(p + 4) = make_float4(f.v[4], f.v[5], f.v[6], f.v[7]); }
; DI void stb8(bf16_t* p, const F8& f) { *(uint4*)p = pack8(f); }
; DI float siluf(float x) { return x / (1.f + __expf(-x)); }
; template <int MODE>
; DI void gemm_epilogue(const float* Cs, int m0, int n0, const Epi& ep) {
;     ...
;     } else if (MODE == 4) {
;         const int mt = m0 >> 7, ch0 = (n0 >> 7) * 64, c8 = (tid & 7) * 8, ch = ch0 + c8;
;         const float* cw = ep.c0;
;         const F8 w0 = ldf8(cw + ch), w1 = ldf8(cw + 2816 + ch), w2 = ldf8(cw + 2 * 2816 + ch);
;         const bool defer01 = (m0 < MP) && ((m0 & 8191) != 0);
; #pragma unroll
;         for (int it = 0; it < 2; ++it) {
;             const int i = (tid >> 3) + 64 * it, r = m0 + i;
;             int sq, pos, len; rowinfo(r, sq, pos, len);
;             const F8 g0 = ldf8(Cs + i * LDC + c8), up = ldf8(Cs + i * LDC + 64 + c8);
;             if (i >= 126) stf8(ep.f0 + ((size_t)mt * 2 + (i - 126)) * 2816 + ch, g0);
;             if (i < 2) { stf8(ep.f1 + ((size_t)mt * 2 + i) * 2816 + ch, g0); stf8(ep.f2 + ((size_t)mt * 2 + i) * 2816 + ch, up); }
;             if (pos >= len - 2) {
;                 float* so = sq < 4 ? ep.out + O_PFF + (((size_t)ep.layer * 4 + sq) * 2 + (pos - (len - 2))) * 2816
;                                    : ep.out + O_SFF + (((size_t)ep.layer * 8 + (sq - 4)) * 2 + (pos - (len - 2))) * 2816;
;                 stf8(so + ch, g0);
;             }
;             if (i < 2 && defer01) continue;
;             F8 g1, g2;
;             const float* hist = sq >= 4 ? ep.c1 + ((size_t)ep.layer * 8 + (sq - 4)) * 2 * 2816 + ch : nullptr;
;             if (pos >= 1) g1 = ldf8(Cs + (i - 1) * LDC + c8);
;             else if (hist) g1 = ldf8(hist + 2816);
;             else { for (int e = 0; e < 8; ++e) g1.v[e] = 0.f; }
;             if (pos >= 2) g2 = ldf8(Cs + (i - 2) * LDC + c8);
;             else if (hist) g2 = ldf8(hist + (size_t)pos * 2816);
;             else { for (int e = 0; e < 8; ++e) g2.v[e] = 0.f; }
;             F8 o;
; #pragma unroll
;             for (int e = 0; e < 8; ++e) o.v[e] = siluf(w0.v[e] * g2.v[e] + w1.v[e] * g1.v[e] + w2.v[e] * g0.v[e]) * up.v[e];
;             stb8(ep.b0 + (size_t)r * 2816 + ch, o);
.Lffn_fast:
	s_lshl_b32 s54, s27, 8
	s_lshl_b32 s30, s26, 7
	s_lshl_b32 s31, s27, 2
	v_bfe_u32 v64, v250, 2, 3
	v_mov_b32_e32 v65, 0x31130220
	v_lshlrev_b32_e32 v64, 2, v64
	v_bfe_u32 v66, v250, 5, 1
	v_lshrrev_b32_e32 v195, 6, v250
	v_lshrrev_b32_e32 v65, v64, v65
	v_lshlrev_b32_e32 v195, 3, v195
	v_and_b32_e32 v65, 3, v65
	v_lshl_add_u32 v195, v66, 2, v195
	v_bfe_u32 v212, v250, 3, 1
	v_add_u32_e32 v195, v195, v65
	v_and_b32_e32 v67, 3, v250
	v_lshlrev_b32_e32 v212, 5, v212
	v_lshl_or_b32 v212, v67, 3, v212
	v_add_u32_e32 v64, s30, v212
	v_add_u32_e32 v65, s54, v195
	s_movk_i32 s0, 0x1600
	v_add_u32_e32 v66, s31, v195
	v_mul_lo_u32 v65, v65, s0
	v_mul_lo_u32 v66, v66, s3
	v_mul_u32_u24_e32 v197, 0x210, v195
	v_lshl_add_u32 v65, v64, 1, v65
	v_lshlrev_b32_e32 v64, 2, v64
	v_lshl_add_u32 v67, v212, 2, 16
	v_add_u32_e32 v66, v66, v64
	v_add_u32_e32 v197, v197, v67
	v_cmp_lt_u32_e64 s[40:41], 1, v195
	v_cmp_gt_u32_e64 s[42:43], 2, v195
	v_cmp_lt_u32_e64 s[44:45], 61, v195
	v_add_u32_e32 v196, 0xfffffbe0, v197
	v_max_i32_e32 v196, v196, v67
	s_mov_b32 s30, 0xbfb8aa3b
	s_mov_b32 s31, 0xbfb8aa3b
	global_load_dwordx4 v[128:131], v64, s[6:7] offset:0
	global_load_dwordx4 v[132:135], v64, s[6:7] offset:16
	global_load_dwordx4 v[136:139], v64, s[14:15] offset:0
	global_load_dwordx4 v[140:143], v64, s[14:15] offset:16
	global_load_dwordx4 v[144:147], v64, s[18:19] offset:0
	global_load_dwordx4 v[148:151], v64, s[18:19] offset:16
	ds_write_b128 v194, v[96:99]
	ds_write_b128 v194, v[100:103] offset:64
	ds_write_b128 v194, v[104:107] offset:8448
	ds_write_b128 v194, v[108:111] offset:8512
	ds_write_b128 v194, v[112:115] offset:16896
	ds_write_b128 v194, v[116:119] offset:16960
	ds_write_b128 v194, v[120:123] offset:25344
	ds_write_b128 v194, v[124:127] offset:25408
	s_waitcnt lgkmcnt(0)
	s_barrier
	ds_read_b128 v[96:99], v197
	ds_read_b128 v[100:103], v197 offset:16
	ds_read_b128 v[112:115], v196 offset:528
	ds_read_b128 v[116:119], v196 offset:544
	ds_read_b128 v[120:123], v196
	ds_read_b128 v[124:127], v196 offset:16
	ds_read_b128 v[104:107], v197 offset:256
	ds_read_b128 v[108:111], v197 offset:272
	s_waitcnt vmcnt(0)
	s_mov_b64 exec, s[42:43]
	s_cbranch_execz .Lffn_f1
	s_waitcnt lgkmcnt(0)
	global_store_dwordx4 v66, v[96:99], s[80:81] offset:0
	global_store_dwordx4 v66, v[100:103], s[80:81] offset:16
	global_store_dwordx4 v66, v[104:107], s[82:83] offset:0
	global_store_dwordx4 v66, v[108:111], s[82:83] offset:16
.Lffn_f1:
	s_mov_b64 exec, -1
	s_waitcnt lgkmcnt(2)
	v_pk_mul_f32 v[120:121], v[128:129], v[120:121]
	v_pk_mul_f32 v[122:123], v[130:131], v[122:123]
	v_pk_mul_f32 v[124:125], v[132:133], v[124:125]
	v_pk_mul_f32 v[126:127], v[134:135], v[126:127]
	v_pk_fma_f32 v[120:121], v[136:137], v[112:113], v[120:121]
	v_pk_fma_f32 v[122:123], v[138:139], v[114:115], v[122:123]
	v_pk_fma_f32 v[124:125], v[140:141], v[116:117], v[124:125]
	v_pk_fma_f32 v[126:127], v[142:143], v[118:119], v[126:127]
	v_pk_fma_f32 v[120:121], v[144:145], v[96:97], v[120:121]
	v_pk_fma_f32 v[122:123], v[146:147], v[98:99], v[122:123]
	v_pk_fma_f32 v[124:125], v[148:149], v[100:101], v[124:125]
	v_pk_fma_f32 v[126:127], v[150:151], v[102:103], v[126:127]
	v_pk_mul_f32 v[152:153], v[120:121], s[30:31]
	v_pk_mul_f32 v[154:155], v[122:123], s[30:31]
	v_pk_mul_f32 v[164:165], v[124:125], s[30:31]
	v_pk_mul_f32 v[166:167], v[126:127], s[30:31]
	s_waitcnt lgkmcnt(0)
	v_pk_mul_f32 v[120:121], v[104:105], v[120:121]
	v_pk_mul_f32 v[122:123], v[106:107], v[122:123]
	v_pk_mul_f32 v[124:125], v[108:109], v[124:125]
	v_pk_mul_f32 v[126:127], v[110:111], v[126:127]
	v_exp_f32_e32 v152, v152
	v_exp_f32_e32 v153, v153
	v_exp_f32_e32 v154, v154
	v_exp_f32_e32 v155, v155
	v_exp_f32_e32 v164, v164
	v_exp_f32_e32 v165, v165
	v_exp_f32_e32 v166, v166
	v_exp_f32_e32 v167, v167
	v_pk_add_f32 v[152:153], v[152:153], 1.0 op_sel_hi:[1,0]
	v_pk_add_f32 v[154:155], v[154:155], 1.0 op_sel_hi:[1,0]
	v_pk_add_f32 v[164:165], v[164:165], 1.0 op_sel_hi:[1,0]
	v_pk_add_f32 v[166:167], v[166:167], 1.0 op_sel_hi:[1,0]
	v_rcp_f32_e32 v152, v152
	v_rcp_f32_e32 v153, v153
	v_rcp_f32_e32 v154, v154
	v_rcp_f32_e32 v155, v155
	v_rcp_f32_e32 v164, v164
	v_rcp_f32_e32 v165, v165
	v_rcp_f32_e32 v166, v166
	v_rcp_f32_e32 v167, v167
	v_pk_mul_f32 v[120:121], v[120:121], v[152:153]
	v_pk_mul_f32 v[122:123], v[122:123], v[154:155]
	v_pk_mul_f32 v[124:125], v[124:125], v[164:165]
	v_pk_mul_f32 v[126:127], v[126:127], v[166:167]
	v_cvt_pk_bf16_f32 v152, v120, v121
	v_cvt_pk_bf16_f32 v153, v122, v123
	v_cvt_pk_bf16_f32 v154, v124, v125
	v_cvt_pk_bf16_f32 v155, v126, v127
	s_mov_b64 exec, s[40:41]
	global_store_dwordx4 v65, v[152:155], s[84:85] offset:0
	s_mov_b64 exec, -1
	ds_read_b128 v[96:99], v197 offset:33792
	ds_read_b128 v[100:103], v197 offset:33808
	ds_read_b128 v[112:115], v197 offset:33264
	ds_read_b128 v[116:119], v197 offset:33280
	ds_read_b128 v[120:123], v197 offset:32736
	ds_read_b128 v[124:127], v197 offset:32752
	ds_read_b128 v[104:107], v197 offset:34048
	ds_read_b128 v[108:111], v197 offset:34064
	v_add_u32_e32 v67, 0x58000, v65
	s_mov_b64 exec, s[44:45]
	s_cbranch_execz .Lffn_f2
	v_add_u32_e32 v212, 0xfff55800, v66
	s_waitcnt lgkmcnt(6)
	global_store_dwordx4 v212, v[96:99], s[72:73] offset:0
	global_store_dwordx4 v212, v[100:103], s[72:73] offset:16
; DI void stf8(float* p, const F8& f) { *(float4*)p = make_float4(f.v[0], f.v[1], f.v[2], f.v[3]); *(float4*)(p + 4) = make_float4(f.v[4], f.v[5], f.v[6], f.v[7]); }
; DI void stb8(bf16_t* p, const F8& f) { *(uint4*)p = pack8(f); }
; DI float siluf(float x) { return x / (1.f + __expf(-x)); }
; template <int MODE>
; DI void gemm_epilogue(const float* Cs, int m0, int n0, const Epi& ep) {
;     ...
;             const F8 g0 = ldf8(Cs + i * LDC + c8), up = ldf8(Cs + i * LDC + 64 + c8);
;             if (i >= 126) stf8(ep.f0 + ((size_t)mt * 2 + (i - 126)) * 2816 + ch, g0);
;             if (i < 2) { stf8(ep.f1 + ((size_t)mt * 2 + i) * 2816 + ch, g0); stf8(ep.f2 + ((size_t)mt * 2 + i) * 2816 + ch, up); }
;             if (pos >= len - 2) {
;                 float* so = sq < 4 ? ep.out + O_PFF + (((size_t)ep.layer * 4 + sq) * 2 + (pos - (len - 2))) * 2816
;                                    : ep.out + O_SFF + (((size_t)ep.layer * 8 + (sq - 4)) * 2 + (pos - (len - 2))) * 2816;
;                 stf8(so + ch, g0);
;             }
;             if (i < 2 && defer01) continue;
;             F8 g1, g2;
;             const float* hist = sq >= 4 ? ep.c1 + ((size_t)ep.layer * 8 + (sq - 4)) * 2 * 2816 + ch : nullptr;
;             if (pos >= 1) g1 = ldf8(Cs + (i - 1) * LDC + c8);
;             else if (hist) g1 = ldf8(hist + 2816);
;             else { for (int e = 0; e < 8; ++e) g1.v[e] = 0.f; }
;             if (pos >= 2) g2 = ldf8(Cs + (i - 2) * LDC + c8);
;             else if (hist) g2 = ldf8(hist + (size_t)pos * 2816);
;             else { for (int e = 0; e < 8; ++e) g2.v[e] = 0.f; }
;             F8 o;
; #pragma unroll
;             for (int e = 0; e < 8; ++e) o.v[e] = siluf(w0.v[e] * g2.v[e] + w1.v[e] * g1.v[e] + w2.v[e] * g0.v[e]) * up.v[e];
;             stb8(ep.b0 + (size_t)r * 2816 + ch, o);
.Lffn_f2:
	s_mov_b64 exec, -1
	s_waitcnt lgkmcnt(2)
	v_pk_mul_f32 v[120:121], v[128:129], v[120:121]
	v_pk_mul_f32 v[122:123], v[130:131], v[122:123]
	v_pk_mul_f32 v[124:125], v[132:133], v[124:125]
	v_pk_mul_f32 v[126:127], v[134:135], v[126:127]
	v_pk_fma_f32 v[120:121], v[136:137], v[112:113], v[120:121]
	v_pk_fma_f32 v[122:123], v[138:139], v[114:115], v[122:123]
	v_pk_fma_f32 v[124:125], v[140:141], v[116:117], v[124:125]
	v_pk_fma_f32 v[126:127], v[142:143], v[118:119], v[126:127]
	v_pk_fma_f32 v[120:121], v[144:145], v[96:97], v[120:121]
	v_pk_fma_f32 v[122:123], v[146:147], v[98:99], v[122:123]
	v_pk_fma_f32 v[124:125], v[148:149], v[100:101], v[124:125]
	v_pk_fma_f32 v[126:127], v[150:151], v[102:103], v[126:127]
	v_pk_mul_f32 v[152:153], v[120:121], s[30:31]
	v_pk_mul_f32 v[154:155], v[122:123], s[30:31]
	v_pk_mul_f32 v[164:165], v[124:125], s[30:31]
	v_pk_mul_f32 v[166:167], v[126:127], s[30:31]
	s_waitcnt lgkmcnt(0)
	v_pk_mul_f32 v[120:121], v[104:105], v[120:121]
	v_pk_mul_f32 v[122:123], v[106:107], v[122:123]
	v_pk_mul_f32 v[124:125], v[108:109], v[124:125]
	v_pk_mul_f32 v[126:127], v[110:111], v[126:127]
	v_exp_f32_e32 v152, v152
	v_exp_f32_e32 v153, v153
	v_exp_f32_e32 v154, v154
	v_exp_f32_e32 v155, v155
	v_exp_f32_e32 v164, v164
	v_exp_f32_e32 v165, v165
	v_exp_f32_e32 v166, v166
	v_exp_f32_e32 v167, v167
	v_pk_add_f32 v[152:153], v[152:153], 1.0 op_sel_hi:[1,0]
	v_pk_add_f32 v[154:155], v[154:155], 1.0 op_sel_hi:[1,0]
	v_pk_add_f32 v[164:165], v[164:165], 1.0 op_sel_hi:[1,0]
	v_pk_add_f32 v[166:167], v[166:167], 1.0 op_sel_hi:[1,0]
	v_rcp_f32_e32 v152, v152
	v_rcp_f32_e32 v153, v153
	v_rcp_f32_e32 v154, v154
	v_rcp_f32_e32 v155, v155
	v_rcp_f32_e32 v164, v164
	v_rcp_f32_e32 v165, v165
	v_rcp_f32_e32 v166, v166
	v_rcp_f32_e32 v167, v167
	v_pk_mul_f32 v[120:121], v[120:121], v[152:153]
	v_pk_mul_f32 v[122:123], v[122:123], v[154:155]
	v_pk_mul_f32 v[124:125], v[124:125], v[164:165]
	v_pk_mul_f32 v[126:127], v[126:127], v[166:167]
	v_cvt_pk_bf16_f32 v152, v120, v121
	v_cvt_pk_bf16_f32 v153, v122, v123
	v_cvt_pk_bf16_f32 v154, v124, v125
	v_cvt_pk_bf16_f32 v155, v126, v127
	global_store_dwordx4 v67, v[152:155], s[84:85] offset:0
	global_load_dwordx4 v[128:131], v64, s[6:7] offset:256
	global_load_dwordx4 v[132:135], v64, s[6:7] offset:272
	global_load_dwordx4 v[136:139], v64, s[14:15] offset:256
	global_load_dwordx4 v[140:143], v64, s[14:15] offset:272
	global_load_dwordx4 v[144:147], v64, s[18:19] offset:256
	global_load_dwordx4 v[148:151], v64, s[18:19] offset:272
	s_barrier
	ds_write_b128 v194, v[222:225]
	ds_write_b128 v194, v[68:71] offset:64
	ds_write_b128 v194, v[72:75] offset:8448
	ds_write_b128 v194, v[76:79] offset:8512
	ds_write_b128 v194, v[80:83] offset:16896
	ds_write_b128 v194, v[84:87] offset:16960
	ds_write_b128 v194, v[88:91] offset:25344
	ds_write_b128 v194, v[92:95] offset:25408
	s_waitcnt lgkmcnt(0)
	s_barrier
	ds_read_b128 v[96:99], v197
	ds_read_b128 v[100:103], v197 offset:16
	ds_read_b128 v[112:115], v196 offset:528
	ds_read_b128 v[116:119], v196 offset:544
	ds_read_b128 v[120:123], v196
	ds_read_b128 v[124:127], v196 offset:16
	ds_read_b128 v[104:107], v197 offset:256
	ds_read_b128 v[108:111], v197 offset:272
	s_waitcnt vmcnt(0)
	s_mov_b64 exec, s[42:43]
	s_cbranch_execz .Lffn_f3
	s_waitcnt lgkmcnt(0)
	global_store_dwordx4 v66, v[96:99], s[80:81] offset:256
	global_store_dwordx4 v66, v[100:103], s[80:81] offset:272
	global_store_dwordx4 v66, v[104:107], s[82:83] offset:256
	global_store_dwordx4 v66, v[108:111], s[82:83] offset:272
.Lffn_f3:
	s_mov_b64 exec, -1
	s_waitcnt lgkmcnt(2)
	v_pk_mul_f32 v[120:121], v[128:129], v[120:121]
	v_pk_mul_f32 v[122:123], v[130:131], v[122:123]
	v_pk_mul_f32 v[124:125], v[132:133], v[124:125]
	v_pk_mul_f32 v[126:127], v[134:135], v[126:127]
	v_pk_fma_f32 v[120:121], v[136:137], v[112:113], v[120:121]
	v_pk_fma_f32 v[122:123], v[138:139], v[114:115], v[122:123]
	v_pk_fma_f32 v[124:125], v[140:141], v[116:117], v[124:125]
	v_pk_fma_f32 v[126:127], v[142:143], v[118:119], v[126:127]
	v_pk_fma_f32 v[120:121], v[144:145], v[96:97], v[120:121]
	v_pk_fma_f32 v[122:123], v[146:147], v[98:99], v[122:123]
	v_pk_fma_f32 v[124:125], v[148:149], v[100:101], v[124:125]
	v_pk_fma_f32 v[126:127], v[150:151], v[102:103], v[126:127]
	v_pk_mul_f32 v[152:153], v[120:121], s[30:31]
	v_pk_mul_f32 v[154:155], v[122:123], s[30:31]
	v_pk_mul_f32 v[164:165], v[124:125], s[30:31]
	v_pk_mul_f32 v[166:167], v[126:127], s[30:31]
	s_waitcnt lgkmcnt(0)
	v_pk_mul_f32 v[120:121], v[104:105], v[120:121]
	v_pk_mul_f32 v[122:123], v[106:107], v[122:123]
	v_pk_mul_f32 v[124:125], v[108:109], v[124:125]
	v_pk_mul_f32 v[126:127], v[110:111], v[126:127]
	v_exp_f32_e32 v152, v152
	v_exp_f32_e32 v153, v153
	v_exp_f32_e32 v154, v154
	v_exp_f32_e32 v155, v155
	v_exp_f32_e32 v164, v164
	v_exp_f32_e32 v165, v165
	v_exp_f32_e32 v166, v166
	v_exp_f32_e32 v167, v167
	v_pk_add_f32 v[152:153], v[152:153], 1.0 op_sel_hi:[1,0]
	v_pk_add_f32 v[154:155], v[154:155], 1.0 op_sel_hi:[1,0]
	v_pk_add_f32 v[164:165], v[164:165], 1.0 op_sel_hi:[1,0]
	v_pk_add_f32 v[166:167], v[166:167], 1.0 op_sel_hi:[1,0]
	v_rcp_f32_e32 v152, v152
	v_rcp_f32_e32 v153, v153
	v_rcp_f32_e32 v154, v154
	v_rcp_f32_e32 v155, v155
	v_rcp_f32_e32 v164, v164
	v_rcp_f32_e32 v165, v165
	v_rcp_f32_e32 v166, v166
	v_rcp_f32_e32 v167, v167
	v_pk_mul_f32 v[120:121], v[120:121], v[152:153]
	v_pk_mul_f32 v[122:123], v[122:123], v[154:155]
	v_pk_mul_f32 v[124:125], v[124:125], v[164:165]
	v_pk_mul_f32 v[126:127], v[126:127], v[166:167]
	v_cvt_pk_bf16_f32 v152, v120, v121
	v_cvt_pk_bf16_f32 v153, v122, v123
	v_cvt_pk_bf16_f32 v154, v124, v125
	v_cvt_pk_bf16_f32 v155, v126, v127
	s_mov_b64 exec, s[40:41]
	global_store_dwordx4 v65, v[152:155], s[84:85] offset:128
	s_mov_b64 exec, -1
	ds_read_b128 v[96:99], v197 offset:33792
	ds_read_b128 v[100:103], v197 offset:33808
	ds_read_b128 v[112:115], v197 offset:33264
	ds_read_b128 v[116:119], v197 offset:33280
	ds_read_b128 v[120:123], v197 offset:32736
	ds_read_b128 v[124:127], v197 offset:32752
	ds_read_b128 v[104:107], v197 offset:34048
	ds_read_b128 v[108:111], v197 offset:34064
	v_add_u32_e32 v67, 0x58000, v65
	s_mov_b64 exec, s[44:45]
	s_cbranch_execz .Lffn_f4
	v_add_u32_e32 v212, 0xfff55800, v66
	s_waitcnt lgkmcnt(6)
	global_store_dwordx4 v212, v[96:99], s[72:73] offset:256
	global_store_dwordx4 v212, v[100:103], s[72:73] offset:272
; DI void stf8(float* p, const F8& f) { *(float4*)p = make_float4(f.v[0], f.v[1], f.v[2], f.v[3]); *(float4*)(p + 4) = make_float4(f.v[4], f.v[5], f.v[6], f.v[7]); }
; DI void stb8(bf16_t* p, const F8& f) { *(uint4*)p = pack8(f); }
; DI float siluf(float x) { return x / (1.f + __expf(-x)); }
; template <int MODE>
; DI void gemm_epilogue(const float* Cs, int m0, int n0, const Epi& ep) {
;     ...
;             const F8 g0 = ldf8(Cs + i * LDC + c8), up = ldf8(Cs + i * LDC + 64 + c8);
;             if (i >= 126) stf8(ep.f0 + ((size_t)mt * 2 + (i - 126)) * 2816 + ch, g0);
;             if (i < 2) { stf8(ep.f1 + ((size_t)mt * 2 + i) * 2816 + ch, g0); stf8(ep.f2 + ((size_t)mt * 2 + i) * 2816 + ch, up); }
;             if (pos >= len - 2) {
;                 float* so = sq < 4 ? ep.out + O_PFF + (((size_t)ep.layer * 4 + sq) * 2 + (pos - (len - 2))) * 2816
;                                    : ep.out + O_SFF + (((size_t)ep.layer * 8 + (sq - 4)) * 2 + (pos - (len - 2))) * 2816;
;                 stf8(so + ch, g0);
;             }
;             if (i < 2 && defer01) continue;
;             F8 g1, g2;
;             const float* hist = sq >= 4 ? ep.c1 + ((size_t)ep.layer * 8 + (sq - 4)) * 2 * 2816 + ch : nullptr;
;             if (pos >= 1) g1 = ldf8(Cs + (i - 1) * LDC + c8);
;             else if (hist) g1 = ldf8(hist + 2816);
;             else { for (int e = 0; e < 8; ++e) g1.v[e] = 0.f; }
;             if (pos >= 2) g2 = ldf8(Cs + (i - 2) * LDC + c8);
;             else if (hist) g2 = ldf8(hist + (size_t)pos * 2816);
;             else { for (int e = 0; e < 8; ++e) g2.v[e] = 0.f; }
;             F8 o;
; #pragma unroll
;             for (int e = 0; e < 8; ++e) o.v[e] = siluf(w0.v[e] * g2.v[e] + w1.v[e] * g1.v[e] + w2.v[e] * g0.v[e]) * up.v[e];
;             stb8(ep.b0 + (size_t)r * 2816 + ch, o);
.Lffn_f4:
	s_mov_b64 exec, -1
	s_waitcnt lgkmcnt(2)
	v_pk_mul_f32 v[120:121], v[128:129], v[120:121]
	v_pk_mul_f32 v[122:123], v[130:131], v[122:123]
	v_pk_mul_f32 v[124:125], v[132:133], v[124:125]
	v_pk_mul_f32 v[126:127], v[134:135], v[126:127]
	v_pk_fma_f32 v[120:121], v[136:137], v[112:113], v[120:121]
	v_pk_fma_f32 v[122:123], v[138:139], v[114:115], v[122:123]
	v_pk_fma_f32 v[124:125], v[140:141], v[116:117], v[124:125]
	v_pk_fma_f32 v[126:127], v[142:143], v[118:119], v[126:127]
	v_pk_fma_f32 v[120:121], v[144:145], v[96:97], v[120:121]
	v_pk_fma_f32 v[122:123], v[146:147], v[98:99], v[122:123]
	v_pk_fma_f32 v[124:125], v[148:149], v[100:101], v[124:125]
	v_pk_fma_f32 v[126:127], v[150:151], v[102:103], v[126:127]
	v_pk_mul_f32 v[152:153], v[120:121], s[30:31]
	v_pk_mul_f32 v[154:155], v[122:123], s[30:31]
	v_pk_mul_f32 v[164:165], v[124:125], s[30:31]
	v_pk_mul_f32 v[166:167], v[126:127], s[30:31]
	s_waitcnt lgkmcnt(0)
	v_pk_mul_f32 v[120:121], v[104:105], v[120:121]
	v_pk_mul_f32 v[122:123], v[106:107], v[122:123]
	v_pk_mul_f32 v[124:125], v[108:109], v[124:125]
	v_pk_mul_f32 v[126:127], v[110:111], v[126:127]
	v_exp_f32_e32 v152, v152
	v_exp_f32_e32 v153, v153
	v_exp_f32_e32 v154, v154
	v_exp_f32_e32 v155, v155
	v_exp_f32_e32 v164, v164
	v_exp_f32_e32 v165, v165
	v_exp_f32_e32 v166, v166
	v_exp_f32_e32 v167, v167
	v_pk_add_f32 v[152:153], v[152:153], 1.0 op_sel_hi:[1,0]
	v_pk_add_f32 v[154:155], v[154:155], 1.0 op_sel_hi:[1,0]
	v_pk_add_f32 v[164:165], v[164:165], 1.0 op_sel_hi:[1,0]
	v_pk_add_f32 v[166:167], v[166:167], 1.0 op_sel_hi:[1,0]
	v_rcp_f32_e32 v152, v152
	v_rcp_f32_e32 v153, v153
	v_rcp_f32_e32 v154, v154
	v_rcp_f32_e32 v155, v155
	v_rcp_f32_e32 v164, v164
	v_rcp_f32_e32 v165, v165
	v_rcp_f32_e32 v166, v166
	v_rcp_f32_e32 v167, v167
	v_pk_mul_f32 v[120:121], v[120:121], v[152:153]
	v_pk_mul_f32 v[122:123], v[122:123], v[154:155]
	v_pk_mul_f32 v[124:125], v[124:125], v[164:165]
	v_pk_mul_f32 v[126:127], v[126:127], v[166:167]
	v_cvt_pk_bf16_f32 v152, v120, v121
	v_cvt_pk_bf16_f32 v153, v122, v123
	v_cvt_pk_bf16_f32 v154, v124, v125
	v_cvt_pk_bf16_f32 v155, v126, v127
	global_store_dwordx4 v67, v[152:155], s[84:85] offset:128
	global_load_dwordx4 v[128:131], v64, s[6:7] offset:0
	global_load_dwordx4 v[132:135], v64, s[6:7] offset:16
	global_load_dwordx4 v[136:139], v64, s[14:15] offset:0
	global_load_dwordx4 v[140:143], v64, s[14:15] offset:16
	global_load_dwordx4 v[144:147], v64, s[18:19] offset:0
	global_load_dwordx4 v[148:151], v64, s[18:19] offset:16
	s_barrier
	ds_write_b128 v194, v[32:35]
	ds_write_b128 v194, v[36:39] offset:64
	ds_write_b128 v194, v[40:43] offset:8448
	ds_write_b128 v194, v[44:47] offset:8512
	ds_write_b128 v194, v[48:51] offset:16896
	ds_write_b128 v194, v[52:55] offset:16960
	ds_write_b128 v194, v[56:59] offset:25344
	ds_write_b128 v194, v[60:63] offset:25408
	s_waitcnt lgkmcnt(0)
	s_barrier
	ds_read_b128 v[96:99], v197
	ds_read_b128 v[100:103], v197 offset:16
	ds_read_b128 v[112:115], v196 offset:528
	ds_read_b128 v[116:119], v196 offset:544
	ds_read_b128 v[120:123], v196
	ds_read_b128 v[124:127], v196 offset:16
	ds_read_b128 v[104:107], v197 offset:256
	ds_read_b128 v[108:111], v197 offset:272
	v_add_u32_e32 v67, 0xb0000, v65
	s_waitcnt vmcnt(0)
	s_mov_b64 exec, s[42:43]
	s_cbranch_execz .Lffn_f5
	v_add_u32_e32 v212, 0x5800, v66
	s_waitcnt lgkmcnt(0)
	global_store_dwordx4 v212, v[96:99], s[80:81] offset:0
	global_store_dwordx4 v212, v[100:103], s[80:81] offset:16
	global_store_dwordx4 v212, v[104:107], s[82:83] offset:0
	global_store_dwordx4 v212, v[108:111], s[82:83] offset:16
.Lffn_f5:
	s_mov_b64 exec, -1
	s_waitcnt lgkmcnt(2)
	v_pk_mul_f32 v[120:121], v[128:129], v[120:121]
	v_pk_mul_f32 v[122:123], v[130:131], v[122:123]
	v_pk_mul_f32 v[124:125], v[132:133], v[124:125]
	v_pk_mul_f32 v[126:127], v[134:135], v[126:127]
	v_pk_fma_f32 v[120:121], v[136:137], v[112:113], v[120:121]
	v_pk_fma_f32 v[122:123], v[138:139], v[114:115], v[122:123]
	v_pk_fma_f32 v[124:125], v[140:141], v[116:117], v[124:125]
	v_pk_fma_f32 v[126:127], v[142:143], v[118:119], v[126:127]
	v_pk_fma_f32 v[120:121], v[144:145], v[96:97], v[120:121]
	v_pk_fma_f32 v[122:123], v[146:147], v[98:99], v[122:123]
	v_pk_fma_f32 v[124:125], v[148:149], v[100:101], v[124:125]
	v_pk_fma_f32 v[126:127], v[150:151], v[102:103], v[126:127]
	v_pk_mul_f32 v[152:153], v[120:121], s[30:31]
	v_pk_mul_f32 v[154:155], v[122:123], s[30:31]
	v_pk_mul_f32 v[164:165], v[124:125], s[30:31]
	v_pk_mul_f32 v[166:167], v[126:127], s[30:31]
	s_waitcnt lgkmcnt(0)
	v_pk_mul_f32 v[120:121], v[104:105], v[120:121]
	v_pk_mul_f32 v[122:123], v[106:107], v[122:123]
	v_pk_mul_f32 v[124:125], v[108:109], v[124:125]
	v_pk_mul_f32 v[126:127], v[110:111], v[126:127]
	v_exp_f32_e32 v152, v152
	v_exp_f32_e32 v153, v153
	v_exp_f32_e32 v154, v154
	v_exp_f32_e32 v155, v155
	v_exp_f32_e32 v164, v164
	v_exp_f32_e32 v165, v165
	v_exp_f32_e32 v166, v166
	v_exp_f32_e32 v167, v167
	v_pk_add_f32 v[152:153], v[152:153], 1.0 op_sel_hi:[1,0]
	v_pk_add_f32 v[154:155], v[154:155], 1.0 op_sel_hi:[1,0]
	v_pk_add_f32 v[164:165], v[164:165], 1.0 op_sel_hi:[1,0]
	v_pk_add_f32 v[166:167], v[166:167], 1.0 op_sel_hi:[1,0]
	v_rcp_f32_e32 v152, v152
	v_rcp_f32_e32 v153, v153
	v_rcp_f32_e32 v154, v154
	v_rcp_f32_e32 v155, v155
	v_rcp_f32_e32 v164, v164
	v_rcp_f32_e32 v165, v165
	v_rcp_f32_e32 v166, v166
	v_rcp_f32_e32 v167, v167
	v_pk_mul_f32 v[120:121], v[120:121], v[152:153]
	v_pk_mul_f32 v[122:123], v[122:123], v[154:155]
	v_pk_mul_f32 v[124:125], v[124:125], v[164:165]
	v_pk_mul_f32 v[126:127], v[126:127], v[166:167]
	v_cvt_pk_bf16_f32 v152, v120, v121
	v_cvt_pk_bf16_f32 v153, v122, v123
	v_cvt_pk_bf16_f32 v154, v124, v125
	v_cvt_pk_bf16_f32 v155, v126, v127
	s_mov_b64 exec, s[40:41]
	global_store_dwordx4 v67, v[152:155], s[84:85] offset:0
	s_mov_b64 exec, -1
	ds_read_b128 v[96:99], v197 offset:33792
	ds_read_b128 v[100:103], v197 offset:33808
	ds_read_b128 v[112:115], v197 offset:33264
	ds_read_b128 v[116:119], v197 offset:33280
	ds_read_b128 v[120:123], v197 offset:32736
	ds_read_b128 v[124:127], v197 offset:32752
	ds_read_b128 v[104:107], v197 offset:34048
	ds_read_b128 v[108:111], v197 offset:34064
	v_add_u32_e32 v67, 0x108000, v65
	s_mov_b64 exec, s[44:45]
	s_cbranch_execz .Lffn_f6
	v_add_u32_e32 v212, 0xfff5b000, v66
	s_waitcnt lgkmcnt(6)
	global_store_dwordx4 v212, v[96:99], s[72:73] offset:0
	global_store_dwordx4 v212, v[100:103], s[72:73] offset:16
; DI void stf8(float* p, const F8& f) { *(float4*)p = make_float4(f.v[0], f.v[1], f.v[2], f.v[3]); *(float4*)(p + 4) = make_float4(f.v[4], f.v[5], f.v[6], f.v[7]); }
; DI void stb8(bf16_t* p, const F8& f) { *(uint4*)p = pack8(f); }
; DI float siluf(float x) { return x / (1.f + __expf(-x)); }
; template <int MODE>
; DI void gemm_epilogue(const float* Cs, int m0, int n0, const Epi& ep) {
;     ...
;             const F8 g0 = ldf8(Cs + i * LDC + c8), up = ldf8(Cs + i * LDC + 64 + c8);
;             if (i >= 126) stf8(ep.f0 + ((size_t)mt * 2 + (i - 126)) * 2816 + ch, g0);
;             if (i < 2) { stf8(ep.f1 + ((size_t)mt * 2 + i) * 2816 + ch, g0); stf8(ep.f2 + ((size_t)mt * 2 + i) * 2816 + ch, up); }
;             if (pos >= len - 2) {
;                 float* so = sq < 4 ? ep.out + O_PFF + (((size_t)ep.layer * 4 + sq) * 2 + (pos - (len - 2))) * 2816
;                                    : ep.out + O_SFF + (((size_t)ep.layer * 8 + (sq - 4)) * 2 + (pos - (len - 2))) * 2816;
;                 stf8(so + ch, g0);
;             }
;             if (i < 2 && defer01) continue;
;             F8 g1, g2;
;             const float* hist = sq >= 4 ? ep.c1 + ((size_t)ep.layer * 8 + (sq - 4)) * 2 * 2816 + ch : nullptr;
;             if (pos >= 1) g1 = ldf8(Cs + (i - 1) * LDC + c8);
;             else if (hist) g1 = ldf8(hist + 2816);
;             else { for (int e = 0; e < 8; ++e) g1.v[e] = 0.f; }
;             if (pos >= 2) g2 = ldf8(Cs + (i - 2) * LDC + c8);
;             else if (hist) g2 = ldf8(hist + (size_t)pos * 2816);
;             else { for (int e = 0; e < 8; ++e) g2.v[e] = 0.f; }
;             F8 o;
; #pragma unroll
;             for (int e = 0; e < 8; ++e) o.v[e] = siluf(w0.v[e] * g2.v[e] + w1.v[e] * g1.v[e] + w2.v[e] * g0.v[e]) * up.v[e];
;             stb8(ep.b0 + (size_t)r * 2816 + ch, o);
.Lffn_f6:
	s_mov_b64 exec, -1
	s_waitcnt lgkmcnt(2)
	v_pk_mul_f32 v[120:121], v[128:129], v[120:121]
	v_pk_mul_f32 v[122:123], v[130:131], v[122:123]
	v_pk_mul_f32 v[124:125], v[132:133], v[124:125]
	v_pk_mul_f32 v[126:127], v[134:135], v[126:127]
	v_pk_fma_f32 v[120:121], v[136:137], v[112:113], v[120:121]
	v_pk_fma_f32 v[122:123], v[138:139], v[114:115], v[122:123]
	v_pk_fma_f32 v[124:125], v[140:141], v[116:117], v[124:125]
	v_pk_fma_f32 v[126:127], v[142:143], v[118:119], v[126:127]
	v_pk_fma_f32 v[120:121], v[144:145], v[96:97], v[120:121]
	v_pk_fma_f32 v[122:123], v[146:147], v[98:99], v[122:123]
	v_pk_fma_f32 v[124:125], v[148:149], v[100:101], v[124:125]
	v_pk_fma_f32 v[126:127], v[150:151], v[102:103], v[126:127]
	v_pk_mul_f32 v[152:153], v[120:121], s[30:31]
	v_pk_mul_f32 v[154:155], v[122:123], s[30:31]
	v_pk_mul_f32 v[164:165], v[124:125], s[30:31]
	v_pk_mul_f32 v[166:167], v[126:127], s[30:31]
	s_waitcnt lgkmcnt(0)
	v_pk_mul_f32 v[120:121], v[104:105], v[120:121]
	v_pk_mul_f32 v[122:123], v[106:107], v[122:123]
	v_pk_mul_f32 v[124:125], v[108:109], v[124:125]
	v_pk_mul_f32 v[126:127], v[110:111], v[126:127]
	v_exp_f32_e32 v152, v152
	v_exp_f32_e32 v153, v153
	v_exp_f32_e32 v154, v154
	v_exp_f32_e32 v155, v155
	v_exp_f32_e32 v164, v164
	v_exp_f32_e32 v165, v165
	v_exp_f32_e32 v166, v166
	v_exp_f32_e32 v167, v167
	v_pk_add_f32 v[152:153], v[152:153], 1.0 op_sel_hi:[1,0]
	v_pk_add_f32 v[154:155], v[154:155], 1.0 op_sel_hi:[1,0]
	v_pk_add_f32 v[164:165], v[164:165], 1.0 op_sel_hi:[1,0]
	v_pk_add_f32 v[166:167], v[166:167], 1.0 op_sel_hi:[1,0]
	v_rcp_f32_e32 v152, v152
	v_rcp_f32_e32 v153, v153
	v_rcp_f32_e32 v154, v154
	v_rcp_f32_e32 v155, v155
	v_rcp_f32_e32 v164, v164
	v_rcp_f32_e32 v165, v165
	v_rcp_f32_e32 v166, v166
	v_rcp_f32_e32 v167, v167
	v_pk_mul_f32 v[120:121], v[120:121], v[152:153]
	v_pk_mul_f32 v[122:123], v[122:123], v[154:155]
	v_pk_mul_f32 v[124:125], v[124:125], v[164:165]
	v_pk_mul_f32 v[126:127], v[126:127], v[166:167]
	v_cvt_pk_bf16_f32 v152, v120, v121
	v_cvt_pk_bf16_f32 v153, v122, v123
	v_cvt_pk_bf16_f32 v154, v124, v125
	v_cvt_pk_bf16_f32 v155, v126, v127
	global_store_dwordx4 v67, v[152:155], s[84:85] offset:0
	global_load_dwordx4 v[128:131], v64, s[6:7] offset:256
	global_load_dwordx4 v[132:135], v64, s[6:7] offset:272
	global_load_dwordx4 v[136:139], v64, s[14:15] offset:256
	global_load_dwordx4 v[140:143], v64, s[14:15] offset:272
	global_load_dwordx4 v[144:147], v64, s[18:19] offset:256
	global_load_dwordx4 v[148:151], v64, s[18:19] offset:272
	s_barrier
	ds_write_b128 v194, v[0:3]
	ds_write_b128 v194, v[4:7] offset:64
	ds_write_b128 v194, v[8:11] offset:8448
	ds_write_b128 v194, v[12:15] offset:8512
	ds_write_b128 v194, v[16:19] offset:16896
	ds_write_b128 v194, v[20:23] offset:16960
	ds_write_b128 v194, v[24:27] offset:25344
	ds_write_b128 v194, v[28:31] offset:25408
	s_waitcnt lgkmcnt(0)
	s_barrier
	ds_read_b128 v[96:99], v197
	ds_read_b128 v[100:103], v197 offset:16
	ds_read_b128 v[112:115], v196 offset:528
	ds_read_b128 v[116:119], v196 offset:544
	ds_read_b128 v[120:123], v196
	ds_read_b128 v[124:127], v196 offset:16
	ds_read_b128 v[104:107], v197 offset:256
	ds_read_b128 v[108:111], v197 offset:272
	v_add_u32_e32 v67, 0xb0000, v65
	s_waitcnt vmcnt(0)
	s_mov_b64 exec, s[42:43]
	s_cbranch_execz .Lffn_f7
	v_add_u32_e32 v212, 0x5800, v66
	s_waitcnt lgkmcnt(0)
	global_store_dwordx4 v212, v[96:99], s[80:81] offset:256
	global_store_dwordx4 v212, v[100:103], s[80:81] offset:272
	global_store_dwordx4 v212, v[104:107], s[82:83] offset:256
	global_store_dwordx4 v212, v[108:111], s[82:83] offset:272
; DI void stf8(float* p, const F8& f) { *(float4*)p = make_float4(f.v[0], f.v[1], f.v[2], f.v[3]); *(float4*)(p + 4) = make_float4(f.v[4], f.v[5], f.v[6], f.v[7]); }
; DI void stb8(bf16_t* p, const F8& f) { *(uint4*)p = pack8(f); }
; DI float siluf(float x) { return x / (1.f + __expf(-x)); }
; template <int MODE>
; DI void gemm_epilogue(const float* Cs, int m0, int n0, const Epi& ep) {
;     ...
;             const F8 g0 = ldf8(Cs + i * LDC + c8), up = ldf8(Cs + i * LDC + 64 + c8);
;             if (i >= 126) stf8(ep.f0 + ((size_t)mt * 2 + (i - 126)) * 2816 + ch, g0);
;             if (i < 2) { stf8(ep.f1 + ((size_t)mt * 2 + i) * 2816 + ch, g0); stf8(ep.f2 + ((size_t)mt * 2 + i) * 2816 + ch, up); }
;             if (pos >= len - 2) {
;                 float* so = sq < 4 ? ep.out + O_PFF + (((size_t)ep.layer * 4 + sq) * 2 + (pos - (len - 2))) * 2816
;                                    : ep.out + O_SFF + (((size_t)ep.layer * 8 + (sq - 4)) * 2 + (pos - (len - 2))) * 2816;
;                 stf8(so + ch, g0);
;             }
;             if (i < 2 && defer01) continue;
;             F8 g1, g2;
;             const float* hist = sq >= 4 ? ep.c1 + ((size_t)ep.layer * 8 + (sq - 4)) * 2 * 2816 + ch : nullptr;
;             if (pos >= 1) g1 = ldf8(Cs + (i - 1) * LDC + c8);
;             else if (hist) g1 = ldf8(hist + 2816);
;             else { for (int e = 0; e < 8; ++e) g1.v[e] = 0.f; }
;             if (pos >= 2) g2 = ldf8(Cs + (i - 2) * LDC + c8);
;             else if (hist) g2 = ldf8(hist + (size_t)pos * 2816);
;             else { for (int e = 0; e < 8; ++e) g2.v[e] = 0.f; }
;             F8 o;
; #pragma unroll
;             for (int e = 0; e < 8; ++e) o.v[e] = siluf(w0.v[e] * g2.v[e] + w1.v[e] * g1.v[e] + w2.v[e] * g0.v[e]) * up.v[e];
;             stb8(ep.b0 + (size_t)r * 2816 + ch, o);
.Lffn_f7:
	s_mov_b64 exec, -1
	s_waitcnt lgkmcnt(2)
	v_pk_mul_f32 v[120:121], v[128:129], v[120:121]
	v_pk_mul_f32 v[122:123], v[130:131], v[122:123]
	v_pk_mul_f32 v[124:125], v[132:133], v[124:125]
	v_pk_mul_f32 v[126:127], v[134:135], v[126:127]
	v_pk_fma_f32 v[120:121], v[136:137], v[112:113], v[120:121]
	v_pk_fma_f32 v[122:123], v[138:139], v[114:115], v[122:123]
	v_pk_fma_f32 v[124:125], v[140:141], v[116:117], v[124:125]
	v_pk_fma_f32 v[126:127], v[142:143], v[118:119], v[126:127]
	v_pk_fma_f32 v[120:121], v[144:145], v[96:97], v[120:121]
	v_pk_fma_f32 v[122:123], v[146:147], v[98:99], v[122:123]
	v_pk_fma_f32 v[124:125], v[148:149], v[100:101], v[124:125]
	v_pk_fma_f32 v[126:127], v[150:151], v[102:103], v[126:127]
	v_pk_mul_f32 v[152:153], v[120:121], s[30:31]
	v_pk_mul_f32 v[154:155], v[122:123], s[30:31]
	v_pk_mul_f32 v[164:165], v[124:125], s[30:31]
	v_pk_mul_f32 v[166:167], v[126:127], s[30:31]
	s_waitcnt lgkmcnt(0)
	v_pk_mul_f32 v[120:121], v[104:105], v[120:121]
	v_pk_mul_f32 v[122:123], v[106:107], v[122:123]
	v_pk_mul_f32 v[124:125], v[108:109], v[124:125]
	v_pk_mul_f32 v[126:127], v[110:111], v[126:127]
	v_exp_f32_e32 v152, v152
	v_exp_f32_e32 v153, v153
	v_exp_f32_e32 v154, v154
	v_exp_f32_e32 v155, v155
	v_exp_f32_e32 v164, v164
	v_exp_f32_e32 v165, v165
	v_exp_f32_e32 v166, v166
	v_exp_f32_e32 v167, v167
	v_pk_add_f32 v[152:153], v[152:153], 1.0 op_sel_hi:[1,0]
	v_pk_add_f32 v[154:155], v[154:155], 1.0 op_sel_hi:[1,0]
	v_pk_add_f32 v[164:165], v[164:165], 1.0 op_sel_hi:[1,0]
	v_pk_add_f32 v[166:167], v[166:167], 1.0 op_sel_hi:[1,0]
	v_rcp_f32_e32 v152, v152
	v_rcp_f32_e32 v153, v153
	v_rcp_f32_e32 v154, v154
	v_rcp_f32_e32 v155, v155
	v_rcp_f32_e32 v164, v164
	v_rcp_f32_e32 v165, v165
	v_rcp_f32_e32 v166, v166
	v_rcp_f32_e32 v167, v167
	v_pk_mul_f32 v[120:121], v[120:121], v[152:153]
	v_pk_mul_f32 v[122:123], v[122:123], v[154:155]
	v_pk_mul_f32 v[124:125], v[124:125], v[164:165]
	v_pk_mul_f32 v[126:127], v[126:127], v[166:167]
	v_cvt_pk_bf16_f32 v152, v120, v121
	v_cvt_pk_bf16_f32 v153, v122, v123
	v_cvt_pk_bf16_f32 v154, v124, v125
	v_cvt_pk_bf16_f32 v155, v126, v127
	s_mov_b64 exec, s[40:41]
	global_store_dwordx4 v67, v[152:155], s[84:85] offset:128
	s_mov_b64 exec, -1
	ds_read_b128 v[96:99], v197 offset:33792
	ds_read_b128 v[100:103], v197 offset:33808
	ds_read_b128 v[112:115], v197 offset:33264
	ds_read_b128 v[116:119], v197 offset:33280
	ds_read_b128 v[120:123], v197 offset:32736
	ds_read_b128 v[124:127], v197 offset:32752
	ds_read_b128 v[104:107], v197 offset:34048
	ds_read_b128 v[108:111], v197 offset:34064
	v_add_u32_e32 v67, 0x108000, v65
	s_mov_b64 exec, s[44:45]
	s_cbranch_execz .Lffn_f8
	v_add_u32_e32 v212, 0xfff5b000, v66
	s_waitcnt lgkmcnt(6)
	global_store_dwordx4 v212, v[96:99], s[72:73] offset:256
	global_store_dwordx4 v212, v[100:103], s[72:73] offset:272
.Lffn_f8:
	s_mov_b64 exec, -1
	s_waitcnt lgkmcnt(2)
	v_pk_mul_f32 v[120:121], v[128:129], v[120:121]
	v_pk_mul_f32 v[122:123], v[130:131], v[122:123]
	v_pk_mul_f32 v[124:125], v[132:133], v[124:125]
	v_pk_mul_f32 v[126:127], v[134:135], v[126:127]
	v_pk_fma_f32 v[120:121], v[136:137], v[112:113], v[120:121]
	v_pk_fma_f32 v[122:123], v[138:139], v[114:115], v[122:123]
	v_pk_fma_f32 v[124:125], v[140:141], v[116:117], v[124:125]
	v_pk_fma_f32 v[126:127], v[142:143], v[118:119], v[126:127]
	v_pk_fma_f32 v[120:121], v[144:145], v[96:97], v[120:121]
	v_pk_fma_f32 v[122:123], v[146:147], v[98:99], v[122:123]
	v_pk_fma_f32 v[124:125], v[148:149], v[100:101], v[124:125]
	v_pk_fma_f32 v[126:127], v[150:151], v[102:103], v[126:127]
	v_pk_mul_f32 v[152:153], v[120:121], s[30:31]
	v_pk_mul_f32 v[154:155], v[122:123], s[30:31]
	v_pk_mul_f32 v[164:165], v[124:125], s[30:31]
	v_pk_mul_f32 v[166:167], v[126:127], s[30:31]
	s_waitcnt lgkmcnt(0)
	v_pk_mul_f32 v[120:121], v[104:105], v[120:121]
	v_pk_mul_f32 v[122:123], v[106:107], v[122:123]
	v_pk_mul_f32 v[124:125], v[108:109], v[124:125]
	v_pk_mul_f32 v[126:127], v[110:111], v[126:127]
	v_exp_f32_e32 v152, v152
	v_exp_f32_e32 v153, v153
	v_exp_f32_e32 v154, v154
	v_exp_f32_e32 v155, v155
	v_exp_f32_e32 v164, v164
	v_exp_f32_e32 v165, v165
	v_exp_f32_e32 v166, v166
	v_exp_f32_e32 v167, v167
	v_pk_add_f32 v[152:153], v[152:153], 1.0 op_sel_hi:[1,0]
	v_pk_add_f32 v[154:155], v[154:155], 1.0 op_sel_hi:[1,0]
	v_pk_add_f32 v[164:165], v[164:165], 1.0 op_sel_hi:[1,0]
	v_pk_add_f32 v[166:167], v[166:167], 1.0 op_sel_hi:[1,0]
	v_rcp_f32_e32 v152, v152
	v_rcp_f32_e32 v153, v153
	v_rcp_f32_e32 v154, v154
	v_rcp_f32_e32 v155, v155
	v_rcp_f32_e32 v164, v164
	v_rcp_f32_e32 v165, v165
	v_rcp_f32_e32 v166, v166
	v_rcp_f32_e32 v167, v167
	v_pk_mul_f32 v[120:121], v[120:121], v[152:153]
	v_pk_mul_f32 v[122:123], v[122:123], v[154:155]
	v_pk_mul_f32 v[124:125], v[124:125], v[164:165]
	v_pk_mul_f32 v[126:127], v[126:127], v[166:167]
	v_cvt_pk_bf16_f32 v152, v120, v121
	v_cvt_pk_bf16_f32 v153, v122, v123
	v_cvt_pk_bf16_f32 v154, v124, v125
	v_cvt_pk_bf16_f32 v155, v126, v127
	global_store_dwordx4 v67, v[152:155], s[84:85] offset:128
	s_mov_b64 s[0:1], -1
	s_branch .LBB0_1142
